# window branch: relative-position bias reads of a score tile issued up front with counted waits (was read-wait per element)
# speedup vs baseline: 1.0367x; 1.0001x over previous
.LBB0_693:
	s_setprio 1
	ds_read_b128 v[188:191], v176
	ds_read_b128 v[240:243], v176 offset:64
	ds_read_b128 v[248:251], v176 offset:128
	ds_read_b128 v[252:255], v176 offset:192
	s_waitcnt lgkmcnt(3)
	v_mfma_f32_16x16x32_bf16 v[184:187], v[188:191], v[0:3], 0
	v_mfma_f32_16x16x32_bf16 v[128:131], v[188:191], v[16:19], 0
	ds_read_b128 v[188:191], v176 offset:4352
	s_waitcnt lgkmcnt(3)
	v_mfma_f32_16x16x32_bf16 v[184:187], v[240:243], v[4:7], v[184:187]
	v_mfma_f32_16x16x32_bf16 v[128:131], v[240:243], v[20:23], v[128:131]
	ds_read_b128 v[240:243], v176 offset:4416
	s_waitcnt lgkmcnt(3)
	v_mfma_f32_16x16x32_bf16 v[184:187], v[248:251], v[8:11], v[184:187]
	v_mfma_f32_16x16x32_bf16 v[128:131], v[248:251], v[24:27], v[128:131]
	ds_read_b128 v[248:251], v176 offset:4480
	s_waitcnt lgkmcnt(3)
	v_mfma_f32_16x16x32_bf16 v[184:187], v[252:255], v[12:15], v[184:187]
	v_mfma_f32_16x16x32_bf16 v[128:131], v[252:255], v[32:35], v[128:131]
	ds_read_b128 v[252:255], v176 offset:4544
	s_waitcnt lgkmcnt(3)
	v_mfma_f32_16x16x32_bf16 v[140:143], v[188:191], v[0:3], 0
	v_mfma_f32_16x16x32_bf16 v[124:127], v[188:191], v[16:19], 0
	ds_read_b128 v[188:191], v176 offset:8704
	s_waitcnt lgkmcnt(3)
	v_mfma_f32_16x16x32_bf16 v[140:143], v[240:243], v[4:7], v[140:143]
	v_mfma_f32_16x16x32_bf16 v[124:127], v[240:243], v[20:23], v[124:127]
	ds_read_b128 v[240:243], v176 offset:8768
	s_waitcnt lgkmcnt(3)
	v_mfma_f32_16x16x32_bf16 v[140:143], v[248:251], v[8:11], v[140:143]
	v_mfma_f32_16x16x32_bf16 v[124:127], v[248:251], v[24:27], v[124:127]
	ds_read_b128 v[248:251], v176 offset:8832
	s_waitcnt lgkmcnt(3)
	v_mfma_f32_16x16x32_bf16 v[140:143], v[252:255], v[12:15], v[140:143]
	v_mfma_f32_16x16x32_bf16 v[124:127], v[252:255], v[32:35], v[124:127]
	ds_read_b128 v[252:255], v176 offset:8896
	s_waitcnt lgkmcnt(3)
	v_mfma_f32_16x16x32_bf16 v[136:139], v[188:191], v[0:3], 0
	v_mfma_f32_16x16x32_bf16 v[120:123], v[188:191], v[16:19], 0
	ds_read_b128 v[188:191], v176 offset:13056
	s_waitcnt lgkmcnt(3)
	v_mfma_f32_16x16x32_bf16 v[136:139], v[240:243], v[4:7], v[136:139]
	v_mfma_f32_16x16x32_bf16 v[120:123], v[240:243], v[20:23], v[120:123]
	ds_read_b128 v[240:243], v176 offset:13120
	s_waitcnt lgkmcnt(3)
	v_mfma_f32_16x16x32_bf16 v[136:139], v[248:251], v[8:11], v[136:139]
	v_mfma_f32_16x16x32_bf16 v[120:123], v[248:251], v[24:27], v[120:123]
	ds_read_b128 v[248:251], v176 offset:13184
	s_waitcnt lgkmcnt(3)
	v_mfma_f32_16x16x32_bf16 v[136:139], v[252:255], v[12:15], v[136:139]
	v_mfma_f32_16x16x32_bf16 v[120:123], v[252:255], v[32:35], v[120:123]
	ds_read_b128 v[252:255], v176 offset:13248
	s_waitcnt lgkmcnt(3)
	v_mfma_f32_16x16x32_bf16 v[132:135], v[188:191], v[0:3], 0
	v_mfma_f32_16x16x32_bf16 v[116:119], v[188:191], v[16:19], 0
	s_waitcnt lgkmcnt(2)
	v_mfma_f32_16x16x32_bf16 v[132:135], v[240:243], v[4:7], v[132:135]
	v_mfma_f32_16x16x32_bf16 v[116:119], v[240:243], v[20:23], v[116:119]
	s_waitcnt lgkmcnt(1)
	v_mfma_f32_16x16x32_bf16 v[132:135], v[248:251], v[8:11], v[132:135]
	v_mfma_f32_16x16x32_bf16 v[116:119], v[248:251], v[24:27], v[116:119]
	s_waitcnt lgkmcnt(0)
	v_mfma_f32_16x16x32_bf16 v[132:135], v[252:255], v[12:15], v[132:135]
	v_mfma_f32_16x16x32_bf16 v[116:119], v[252:255], v[32:35], v[116:119]
	s_setprio 0
	v_lshl_add_u32 v189, s2, 6, v155
	v_sub_u32_e32 v239, v160, v189
	v_med3_i32 v239, v239, 0, v207
	v_lshl_add_u32 v239, v239, 2, v151
	ds_read_b32 v31, v239 offset:9216
	v_or_b32_e32 v240, 1, v189
	v_sub_u32_e32 v240, v160, v240
	v_med3_i32 v240, v240, 0, v207
	v_lshl_add_u32 v240, v240, 2, v151
	ds_read_b32 v240, v240 offset:9216
	v_or_b32_e32 v241, 2, v189
	v_sub_u32_e32 v241, v160, v241
	v_med3_i32 v241, v241, 0, v207
	v_lshl_add_u32 v241, v241, 2, v151
	ds_read_b32 v241, v241 offset:9216
	v_or_b32_e32 v242, 3, v189
	v_sub_u32_e32 v242, v160, v242
	v_med3_i32 v242, v242, 0, v207
	v_lshl_add_u32 v242, v242, 2, v151
	ds_read_b32 v242, v242 offset:9216
	v_sub_u32_e32 v243, v175, v189
	v_med3_i32 v243, v243, 0, v207
	v_lshl_add_u32 v243, v243, 2, v151
	ds_read_b32 v243, v243 offset:9216
	v_add_u32_e32 v247, 17, v189
	v_sub_u32_e32 v247, v160, v247
	v_med3_i32 v247, v247, 0, v207
	v_lshl_add_u32 v247, v247, 2, v151
	ds_read_b32 v247, v247 offset:9216
	v_add_u32_e32 v248, 18, v189
	v_sub_u32_e32 v248, v160, v248
	v_med3_i32 v248, v248, 0, v207
	v_lshl_add_u32 v248, v248, 2, v151
	ds_read_b32 v248, v248 offset:9216
	v_add_u32_e32 v249, 19, v189
	v_sub_u32_e32 v249, v160, v249
	v_med3_i32 v249, v249, 0, v207
	v_lshl_add_u32 v249, v249, 2, v151
	ds_read_b32 v249, v249 offset:9216
	v_add_u32_e32 v250, 32, v189
	v_sub_u32_e32 v250, v160, v250
	v_med3_i32 v250, v250, 0, v207
	v_lshl_add_u32 v250, v250, 2, v151
	ds_read_b32 v250, v250 offset:9216
	v_add_u32_e32 v251, 33, v189
	v_sub_u32_e32 v251, v160, v251
	v_med3_i32 v251, v251, 0, v207
	v_lshl_add_u32 v251, v251, 2, v151
	ds_read_b32 v251, v251 offset:9216
	v_add_u32_e32 v252, 34, v189
	v_sub_u32_e32 v252, v160, v252
	v_med3_i32 v252, v252, 0, v207
	v_lshl_add_u32 v252, v252, 2, v151
	ds_read_b32 v252, v252 offset:9216
	v_add_u32_e32 v253, 35, v189
	v_sub_u32_e32 v253, v160, v253
	v_med3_i32 v253, v253, 0, v207
	v_lshl_add_u32 v253, v253, 2, v151
	ds_read_b32 v253, v253 offset:9216
	v_add_u32_e32 v254, 48, v189
	v_sub_u32_e32 v254, v160, v254
	v_med3_i32 v254, v254, 0, v207
	v_lshl_add_u32 v254, v254, 2, v151
	ds_read_b32 v254, v254 offset:9216
	v_add_u32_e32 v255, 49, v189
	v_sub_u32_e32 v255, v160, v255
	v_med3_i32 v255, v255, 0, v207
	v_lshl_add_u32 v255, v255, 2, v151
	ds_read_b32 v255, v255 offset:9216
	v_or_b32_e32 v190, 1, v189
	v_sub_u32_e32 v30, v160, v189
	v_sub_u32_e32 v183, v160, v190
	v_cmp_gt_u32_e64 s[8:9], s75, v30
	v_cmp_gt_u32_e32 vcc, s75, v183
	v_or_b32_e32 v191, 2, v189
	v_or_b32_e32 v192, 3, v189
	v_add_u32_e32 v213, 17, v189
	s_waitcnt lgkmcnt(13)
	v_add_f32_e32 v30, v184, v31
	s_waitcnt lgkmcnt(12)
	v_add_f32_e32 v183, v185, v240
	v_sub_u32_e32 v185, v160, v191
	v_cndmask_b32_e32 v184, v208, v183, vcc
	v_cmp_gt_u32_e32 vcc, s75, v185
	v_add_u32_e32 v214, 18, v189
	v_add_u32_e32 v215, 19, v189
	v_add_u32_e32 v216, 32, v189
	v_add_u32_e32 v193, 33, v189
	s_waitcnt lgkmcnt(11)
	v_add_f32_e32 v185, v186, v241
	v_sub_u32_e32 v186, v160, v192
	v_cndmask_b32_e32 v185, v208, v185, vcc
	v_cmp_gt_u32_e32 vcc, s75, v186
	v_cndmask_b32_e64 v30, v208, v30, s[8:9]
	v_max3_f32 v183, v30, s82, v184
	v_add_u32_e32 v194, 34, v189
	v_add_u32_e32 v195, 35, v189
	s_waitcnt lgkmcnt(10)
	v_add_f32_e32 v186, v187, v242
	v_sub_u32_e32 v187, v175, v189
	v_cndmask_b32_e32 v186, v208, v186, vcc
	v_cmp_gt_u32_e32 vcc, s75, v187
	v_max3_f32 v183, v183, v185, v186
	v_add_u32_e32 v209, 48, v189
	v_add_u32_e32 v210, 49, v189
	v_add_u32_e32 v211, 50, v189
	s_waitcnt lgkmcnt(9)
	v_add_f32_e32 v140, v140, v243
	v_sub_u32_e32 v187, v160, v213
	v_cndmask_b32_e32 v140, v208, v140, vcc
	v_cmp_gt_u32_e32 vcc, s75, v187
	v_add_u32_e32 v212, 51, v189
	s_waitcnt lgkmcnt(8)
	v_add_f32_e32 v141, v141, v247
	v_sub_u32_e32 v187, v160, v214
	v_cndmask_b32_e32 v141, v208, v141, vcc
	v_cmp_gt_u32_e32 vcc, s75, v187
	v_max3_f32 v183, v183, v140, v141
	s_waitcnt lgkmcnt(7)
	v_add_f32_e32 v142, v142, v248
	v_sub_u32_e32 v187, v160, v215
	v_cndmask_b32_e32 v142, v208, v142, vcc
	v_cmp_gt_u32_e32 vcc, s75, v187
	s_waitcnt lgkmcnt(6)
	v_add_f32_e32 v143, v143, v249
	v_sub_u32_e32 v187, v160, v216
	v_cndmask_b32_e32 v143, v208, v143, vcc
	v_cmp_gt_u32_e32 vcc, s75, v187
	v_max3_f32 v183, v183, v142, v143
	s_waitcnt lgkmcnt(5)
	v_add_f32_e32 v136, v136, v250
	v_sub_u32_e32 v187, v160, v193
	v_cndmask_b32_e32 v136, v208, v136, vcc
	v_cmp_gt_u32_e32 vcc, s75, v187
	s_waitcnt lgkmcnt(4)
	v_add_f32_e32 v137, v137, v251
	v_cndmask_b32_e32 v187, v208, v137, vcc
	v_max3_f32 v137, v183, v136, v187
	v_sub_u32_e32 v183, v160, v194
	v_cmp_gt_u32_e32 vcc, s75, v183
	s_waitcnt lgkmcnt(3)
	v_add_f32_e32 v138, v138, v252
	v_cndmask_b32_e32 v188, v208, v138, vcc
	v_sub_u32_e32 v138, v160, v195
	v_cmp_gt_u32_e32 vcc, s75, v138
	s_waitcnt lgkmcnt(2)
	v_add_f32_e32 v138, v139, v253
	v_cndmask_b32_e32 v217, v208, v138, vcc
	v_sub_u32_e32 v138, v160, v209
	v_cmp_gt_u32_e32 vcc, s75, v138
	v_max3_f32 v137, v137, v188, v217
	s_waitcnt lgkmcnt(1)
	v_add_f32_e32 v132, v132, v254
	v_cndmask_b32_e32 v218, v208, v132, vcc
	v_sub_u32_e32 v132, v160, v210
	v_cmp_gt_u32_e32 vcc, s75, v132
	s_waitcnt lgkmcnt(0)
	v_add_f32_e32 v132, v133, v255
	v_sub_u32_e32 v133, v160, v211
	v_cndmask_b32_e32 v219, v208, v132, vcc
	v_cmp_gt_u32_e32 vcc, s75, v133
	v_med3_i32 v133, v133, 0, v207
	v_lshl_add_u32 v133, v133, 2, v151
	ds_read_b32 v133, v133 offset:9216
	v_max3_f32 v132, v137, v218, v219
	s_waitcnt lgkmcnt(0)
	v_add_f32_e32 v133, v134, v133
	v_cndmask_b32_e32 v220, v208, v133, vcc
	v_sub_u32_e32 v133, v160, v212
	v_cmp_gt_u32_e32 vcc, s75, v133
	v_med3_i32 v133, v133, 0, v207
	v_lshl_add_u32 v133, v133, 2, v151
	ds_read_b32 v133, v133 offset:9216
	s_waitcnt lgkmcnt(0)
	v_add_f32_e32 v133, v135, v133
	v_cndmask_b32_e32 v135, v208, v133, vcc
	v_max3_f32 v132, v132, v220, v135
	v_mov_b32_e32 v133, v132
	s_nop 1
	v_permlane16_swap_b32_e32 v132, v133
	v_max_f32_e32 v133, v133, v133
	v_max_f32_e32 v132, v132, v132
	v_max_f32_e32 v132, v132, v133
	v_mov_b32_e32 v133, v132
	s_nop 1
	v_permlane32_swap_b32_e32 v132, v133
	v_max3_f32 v183, v29, v132, v133
	v_sub_f32_e32 v29, v29, v183
	v_mul_f32_e32 v221, 0x3fb8aa3b, v29
	v_sub_f32_e32 v29, v30, v183
	v_mul_f32_e32 v29, 0x3fb8aa3b, v29
	v_sub_f32_e32 v132, v184, v183
	v_exp_f32_e32 v29, v29
	v_mul_f32_e32 v132, 0x3fb8aa3b, v132
	v_sub_f32_e32 v133, v185, v183
	v_exp_f32_e32 v132, v132
	v_mul_f32_e32 v133, 0x3fb8aa3b, v133
	v_sub_f32_e32 v134, v186, v183
	v_exp_f32_e32 v133, v133
	v_mul_f32_e32 v134, 0x3fb8aa3b, v134
	v_cmp_lt_f32_e32 vcc, s51, v30
	v_exp_f32_e32 v134, v134
	s_nop 0
	v_cndmask_b32_e32 v29, 0, v29, vcc
	v_cmp_lt_f32_e32 vcc, s51, v184
	v_add_f32_e32 v30, 0, v29
	s_nop 0
	v_cndmask_b32_e32 v132, 0, v132, vcc
	v_cmp_lt_f32_e32 vcc, s51, v185
	v_add_f32_e32 v30, v132, v30
	s_nop 0
	v_cndmask_b32_e32 v133, 0, v133, vcc
	v_cmp_lt_f32_e32 vcc, s51, v186
	v_add_f32_e32 v30, v133, v30
	s_nop 0
	v_cndmask_b32_e32 v137, 0, v134, vcc
	v_sub_f32_e32 v134, v140, v183
	v_mul_f32_e32 v134, 0x3fb8aa3b, v134
	v_exp_f32_e32 v134, v134
	v_cmp_lt_f32_e32 vcc, s51, v140
	v_add_f32_e32 v30, v137, v30
	s_nop 0
	v_cndmask_b32_e32 v138, 0, v134, vcc
	v_sub_f32_e32 v134, v141, v183
	v_mul_f32_e32 v134, 0x3fb8aa3b, v134
	v_exp_f32_e32 v134, v134
	v_cmp_lt_f32_e32 vcc, s51, v141
	v_add_f32_e32 v30, v138, v30
	s_nop 0
	v_cndmask_b32_e32 v141, 0, v134, vcc
	v_sub_f32_e32 v134, v142, v183
	v_mul_f32_e32 v134, 0x3fb8aa3b, v134
	v_exp_f32_e32 v134, v134
	v_cmp_lt_f32_e32 vcc, s51, v142
	v_add_f32_e32 v30, v141, v30
	s_nop 0
	v_cndmask_b32_e32 v142, 0, v134, vcc
	v_sub_f32_e32 v134, v143, v183
	v_mul_f32_e32 v134, 0x3fb8aa3b, v134
	v_exp_f32_e32 v134, v134
	v_cmp_lt_f32_e32 vcc, s51, v143
	v_add_f32_e32 v30, v142, v30
	s_nop 0
	v_cndmask_b32_e32 v185, 0, v134, vcc
	v_sub_f32_e32 v134, v136, v183
	v_cmp_lt_f32_e32 vcc, s51, v136
	v_mul_f32_e32 v134, 0x3fb8aa3b, v134
	v_sub_f32_e32 v136, v187, v183
	v_exp_f32_e32 v134, v134
	v_mul_f32_e32 v136, 0x3fb8aa3b, v136
	v_exp_f32_e32 v136, v136
	v_add_f32_e32 v30, v185, v30
	v_cndmask_b32_e32 v134, 0, v134, vcc
	v_cmp_lt_f32_e32 vcc, s51, v187
	v_add_f32_e32 v30, v134, v30
	s_nop 0
	v_cndmask_b32_e32 v139, 0, v136, vcc
	v_sub_f32_e32 v136, v188, v183
	v_mul_f32_e32 v136, 0x3fb8aa3b, v136
	v_exp_f32_e32 v136, v136
	v_cmp_lt_f32_e32 vcc, s51, v188
	v_add_f32_e32 v30, v139, v30
	s_nop 0
	v_cndmask_b32_e32 v140, 0, v136, vcc
	v_sub_f32_e32 v136, v217, v183
	v_mul_f32_e32 v136, 0x3fb8aa3b, v136
	v_exp_f32_e32 v136, v136
	v_cmp_lt_f32_e32 vcc, s51, v217
	v_add_f32_e32 v30, v140, v30
	s_nop 0
	v_cndmask_b32_e32 v143, 0, v136, vcc
	v_sub_f32_e32 v136, v218, v183
	v_mul_f32_e32 v136, 0x3fb8aa3b, v136
	v_exp_f32_e32 v136, v136
	v_cmp_lt_f32_e32 vcc, s51, v218
	v_add_f32_e32 v30, v143, v30
	s_nop 0
	v_cndmask_b32_e32 v184, 0, v136, vcc
	v_sub_f32_e32 v136, v219, v183
	v_mul_f32_e32 v136, 0x3fb8aa3b, v136
	v_exp_f32_e32 v136, v136
	v_cmp_lt_f32_e32 vcc, s51, v219
	v_add_f32_e32 v30, v184, v30
	s_nop 0
	v_cndmask_b32_e32 v186, 0, v136, vcc
	v_sub_f32_e32 v136, v220, v183
	v_mul_f32_e32 v136, 0x3fb8aa3b, v136
	v_exp_f32_e32 v136, v136
	v_cmp_lt_f32_e32 vcc, s51, v220
	v_add_f32_e32 v30, v186, v30
	s_nop 0
	v_cndmask_b32_e32 v187, 0, v136, vcc
	v_cmp_lt_f32_e32 vcc, s51, v135
	v_sub_f32_e32 v135, v135, v183
	v_mul_f32_e32 v135, 0x3fb8aa3b, v135
	v_exp_f32_e32 v135, v135
	v_add_f32_e32 v30, v187, v30
	v_cndmask_b32_e32 v188, 0, v135, vcc
	v_add_f32_e32 v135, v188, v30
	v_exp_f32_e32 v30, v221
	v_mov_b32_e32 v136, v135
	s_nop 1
	v_permlane16_swap_b32_e32 v135, v136
	v_add_f32_e32 v135, v135, v136
	v_mov_b32_e32 v136, v135
	s_nop 1
	v_permlane32_swap_b32_e32 v135, v136
	v_cmp_neq_f32_e32 vcc, 1.0, v30
	s_cbranch_vccz .LBB0_695
	v_pk_mul_f32 v[98:99], v[98:99], v[30:31] op_sel_hi:[1,0]
	v_pk_mul_f32 v[96:97], v[96:97], v[30:31] op_sel_hi:[1,0]
	v_pk_mul_f32 v[94:95], v[94:95], v[30:31] op_sel_hi:[1,0]
	v_pk_mul_f32 v[92:93], v[92:93], v[30:31] op_sel_hi:[1,0]
	v_pk_mul_f32 v[90:91], v[90:91], v[30:31] op_sel_hi:[1,0]
	v_pk_mul_f32 v[88:89], v[88:89], v[30:31] op_sel_hi:[1,0]
	v_pk_mul_f32 v[86:87], v[86:87], v[30:31] op_sel_hi:[1,0]
	v_pk_mul_f32 v[84:85], v[84:85], v[30:31] op_sel_hi:[1,0]
	v_pk_mul_f32 v[82:83], v[82:83], v[30:31] op_sel_hi:[1,0]
	v_pk_mul_f32 v[80:81], v[80:81], v[30:31] op_sel_hi:[1,0]
	v_pk_mul_f32 v[78:79], v[78:79], v[30:31] op_sel_hi:[1,0]
	v_pk_mul_f32 v[76:77], v[76:77], v[30:31] op_sel_hi:[1,0]
	v_pk_mul_f32 v[74:75], v[74:75], v[30:31] op_sel_hi:[1,0]
	v_pk_mul_f32 v[72:73], v[72:73], v[30:31] op_sel_hi:[1,0]
	v_pk_mul_f32 v[70:71], v[70:71], v[30:31] op_sel_hi:[1,0]
	v_pk_mul_f32 v[68:69], v[68:69], v[30:31] op_sel_hi:[1,0]
.LBB0_695:
	v_sub_u32_e32 v239, v156, v189
	v_med3_i32 v239, v239, 0, v207
	v_lshl_add_u32 v239, v239, 2, v151
	ds_read_b32 v239, v239 offset:9216
	v_sub_u32_e32 v240, v156, v190
	v_med3_i32 v240, v240, 0, v207
	v_lshl_add_u32 v240, v240, 2, v151
	ds_read_b32 v240, v240 offset:9216
	v_sub_u32_e32 v241, v156, v191
	v_med3_i32 v241, v241, 0, v207
	v_lshl_add_u32 v241, v241, 2, v151
	ds_read_b32 v241, v241 offset:9216
	v_sub_u32_e32 v242, v156, v192
	v_med3_i32 v242, v242, 0, v207
	v_lshl_add_u32 v242, v242, 2, v151
	ds_read_b32 v242, v242 offset:9216
	v_sub_u32_e32 v243, v156, v213
	v_med3_i32 v243, v243, 0, v207
	v_lshl_add_u32 v243, v243, 2, v151
	ds_read_b32 v243, v243 offset:9216
	v_sub_u32_e32 v247, v156, v214
	v_med3_i32 v247, v247, 0, v207
	v_lshl_add_u32 v247, v247, 2, v151
	ds_read_b32 v247, v247 offset:9216
	v_sub_u32_e32 v248, v156, v215
	v_med3_i32 v248, v248, 0, v207
	v_lshl_add_u32 v248, v248, 2, v151
	ds_read_b32 v248, v248 offset:9216
	v_sub_u32_e32 v249, v156, v216
	v_med3_i32 v249, v249, 0, v207
	v_lshl_add_u32 v249, v249, 2, v151
	ds_read_b32 v249, v249 offset:9216
	v_sub_u32_e32 v250, v156, v193
	v_med3_i32 v250, v250, 0, v207
	v_lshl_add_u32 v250, v250, 2, v151
	ds_read_b32 v250, v250 offset:9216
	v_sub_u32_e32 v251, v156, v194
	v_med3_i32 v251, v251, 0, v207
	v_lshl_add_u32 v251, v251, 2, v151
	ds_read_b32 v251, v251 offset:9216
	v_sub_u32_e32 v252, v156, v195
	v_med3_i32 v252, v252, 0, v207
	v_lshl_add_u32 v252, v252, 2, v151
	ds_read_b32 v252, v252 offset:9216
	v_sub_u32_e32 v253, v156, v209
	v_med3_i32 v253, v253, 0, v207
	v_lshl_add_u32 v253, v253, 2, v151
	ds_read_b32 v253, v253 offset:9216
	v_sub_u32_e32 v254, v156, v210
	v_med3_i32 v254, v254, 0, v207
	v_lshl_add_u32 v254, v254, 2, v151
	ds_read_b32 v254, v254 offset:9216
	v_sub_u32_e32 v255, v156, v211
	v_med3_i32 v255, v255, 0, v207
	v_lshl_add_u32 v255, v255, 2, v151
	ds_read_b32 v255, v255 offset:9216
	v_sub_u32_e32 v189, v156, v189
	v_cmp_gt_u32_e32 vcc, s75, v189
	v_add_f32_e32 v31, v124, v31
	v_cndmask_b32_e64 v124, v208, v31, s[8:9]
	v_sub_u32_e32 v31, v156, v213
	s_waitcnt lgkmcnt(13)
	v_add_f32_e32 v128, v128, v239
	v_sub_u32_e32 v189, v156, v190
	v_cndmask_b32_e32 v128, v208, v128, vcc
	v_cmp_gt_u32_e32 vcc, s75, v189
	v_sub_u32_e32 v190, v156, v191
	s_waitcnt lgkmcnt(12)
	v_add_f32_e32 v129, v129, v240
	v_cndmask_b32_e32 v129, v208, v129, vcc
	v_cmp_gt_u32_e32 vcc, s75, v190
	v_max3_f32 v189, v128, s82, v129
	s_waitcnt lgkmcnt(11)
	v_add_f32_e32 v130, v130, v241
	v_sub_u32_e32 v190, v156, v192
	v_cndmask_b32_e32 v130, v208, v130, vcc
	v_cmp_gt_u32_e32 vcc, s75, v190
	s_waitcnt lgkmcnt(10)
	v_add_f32_e32 v131, v131, v242
	v_cndmask_b32_e32 v131, v208, v131, vcc
	v_cmp_gt_u32_e32 vcc, s75, v31
	v_max3_f32 v189, v189, v130, v131
	s_waitcnt lgkmcnt(9)
	v_add_f32_e32 v31, v125, v243
	v_cndmask_b32_e32 v125, v208, v31, vcc
	v_max3_f32 v31, v189, v124, v125
	v_sub_u32_e32 v189, v156, v214
	v_cmp_gt_u32_e32 vcc, s75, v189
	s_waitcnt lgkmcnt(8)
	v_add_f32_e32 v126, v126, v247
	v_sub_u32_e32 v189, v156, v215
	v_cndmask_b32_e32 v126, v208, v126, vcc
	v_cmp_gt_u32_e32 vcc, s75, v189
	s_waitcnt lgkmcnt(7)
	v_add_f32_e32 v127, v127, v248
	v_sub_u32_e32 v189, v156, v216
	v_cndmask_b32_e32 v127, v208, v127, vcc
	v_cmp_gt_u32_e32 vcc, s75, v189
	v_max3_f32 v31, v31, v126, v127
	s_waitcnt lgkmcnt(6)
	v_add_f32_e32 v120, v120, v249
	v_sub_u32_e32 v189, v156, v193
	v_cndmask_b32_e32 v120, v208, v120, vcc
	v_cmp_gt_u32_e32 vcc, s75, v189
	s_waitcnt lgkmcnt(5)
	v_add_f32_e32 v121, v121, v250
	v_cndmask_b32_e32 v189, v208, v121, vcc
	v_sub_u32_e32 v121, v156, v194
	v_cmp_gt_u32_e32 vcc, s75, v121
	v_max3_f32 v31, v31, v120, v189
	s_waitcnt lgkmcnt(4)
	v_add_f32_e32 v121, v122, v251
	v_cndmask_b32_e32 v190, v208, v121, vcc
	v_sub_u32_e32 v121, v156, v195
	v_cmp_gt_u32_e32 vcc, s75, v121
	s_waitcnt lgkmcnt(3)
	v_add_f32_e32 v121, v123, v252
	v_cndmask_b32_e32 v123, v208, v121, vcc
	v_sub_u32_e32 v121, v156, v209
	v_cmp_gt_u32_e32 vcc, s75, v121
	v_max3_f32 v31, v31, v190, v123
	s_waitcnt lgkmcnt(2)
	v_add_f32_e32 v116, v116, v253
	v_sub_u32_e32 v121, v156, v210
	v_cndmask_b32_e32 v116, v208, v116, vcc
	v_cmp_gt_u32_e32 vcc, s75, v121
	s_waitcnt lgkmcnt(1)
	v_add_f32_e32 v117, v117, v254
	v_cndmask_b32_e32 v191, v208, v117, vcc
	v_sub_u32_e32 v117, v156, v211
	v_cmp_gt_u32_e32 vcc, s75, v117
	v_max3_f32 v31, v31, v116, v191
	s_waitcnt lgkmcnt(0)
	v_add_f32_e32 v117, v118, v255
	v_cndmask_b32_e32 v192, v208, v117, vcc
	v_sub_u32_e32 v117, v156, v212
	v_cmp_gt_u32_e32 vcc, s75, v117
	v_med3_i32 v117, v117, 0, v207
	v_lshl_add_u32 v117, v117, 2, v151
	ds_read_b32 v117, v117 offset:9216
	s_waitcnt lgkmcnt(0)
	v_add_f32_e32 v117, v119, v117
	v_cndmask_b32_e32 v193, v208, v117, vcc
	v_max3_f32 v31, v31, v192, v193
	v_mov_b32_e32 v117, v31
	s_nop 1
	v_permlane16_swap_b32_e32 v31, v117
	v_max_f32_e32 v117, v117, v117
	v_max_f32_e32 v31, v31, v31
	v_max_f32_e32 v31, v31, v117
	v_mov_b32_e32 v117, v31
	s_nop 1
	v_permlane32_swap_b32_e32 v31, v117
	v_max3_f32 v31, v182, v31, v117
	v_sub_f32_e32 v117, v182, v31
	v_mul_f32_e32 v194, 0x3fb8aa3b, v117
	v_sub_f32_e32 v117, v128, v31
	v_mul_f32_e32 v117, 0x3fb8aa3b, v117
	v_sub_f32_e32 v118, v129, v31
	v_exp_f32_e32 v117, v117
	v_mul_f32_e32 v118, 0x3fb8aa3b, v118
	v_exp_f32_e32 v118, v118
	v_cmp_lt_f32_e32 vcc, s51, v128
	s_nop 1
	v_cndmask_b32_e32 v117, 0, v117, vcc
	v_cmp_lt_f32_e32 vcc, s51, v129
	v_add_f32_e32 v119, 0, v117
	s_nop 0
	v_cndmask_b32_e32 v118, 0, v118, vcc
	v_add_f32_e32 v121, v118, v119
	v_sub_f32_e32 v119, v130, v31
	v_mul_f32_e32 v119, 0x3fb8aa3b, v119
	v_exp_f32_e32 v119, v119
	v_cmp_lt_f32_e32 vcc, s51, v130
	s_nop 1
	v_cndmask_b32_e32 v119, 0, v119, vcc
	v_add_f32_e32 v122, v119, v121
	v_sub_f32_e32 v121, v131, v31
	v_mul_f32_e32 v121, 0x3fb8aa3b, v121
	v_exp_f32_e32 v121, v121
	v_cmp_lt_f32_e32 vcc, s51, v131
	s_nop 1
	v_cndmask_b32_e32 v121, 0, v121, vcc
	v_add_f32_e32 v128, v121, v122
	v_sub_f32_e32 v122, v124, v31
	v_mul_f32_e32 v122, 0x3fb8aa3b, v122
	v_exp_f32_e32 v122, v122
	v_cmp_lt_f32_e32 vcc, s51, v124
	s_nop 1
	v_cndmask_b32_e32 v122, 0, v122, vcc
	v_cmp_lt_f32_e32 vcc, s51, v125
	v_sub_f32_e32 v125, v125, v31
	v_mul_f32_e32 v125, 0x3fb8aa3b, v125
	v_exp_f32_e32 v125, v125
	v_add_f32_e32 v124, v122, v128
	v_cndmask_b32_e32 v128, 0, v125, vcc
	v_sub_f32_e32 v125, v126, v31
	v_mul_f32_e32 v125, 0x3fb8aa3b, v125
	v_exp_f32_e32 v125, v125
	v_cmp_lt_f32_e32 vcc, s51, v126
	v_sub_f32_e32 v126, v190, v31
	v_mul_f32_e32 v126, 0x3fb8aa3b, v126
	v_cndmask_b32_e32 v129, 0, v125, vcc
	v_sub_f32_e32 v125, v127, v31
	v_mul_f32_e32 v125, 0x3fb8aa3b, v125
	v_exp_f32_e32 v125, v125
	v_cmp_lt_f32_e32 vcc, s51, v127
	v_exp_f32_e32 v126, v126
	v_add_f32_e32 v124, v128, v124
	v_cndmask_b32_e32 v131, 0, v125, vcc
	v_cmp_lt_f32_e32 vcc, s51, v120
	v_sub_f32_e32 v120, v120, v31
	v_mul_f32_e32 v120, 0x3fb8aa3b, v120
	v_sub_f32_e32 v125, v189, v31
	v_exp_f32_e32 v120, v120
	v_mul_f32_e32 v125, 0x3fb8aa3b, v125
	v_exp_f32_e32 v125, v125
	v_add_f32_e32 v124, v129, v124
	v_cndmask_b32_e32 v120, 0, v120, vcc
	v_cmp_lt_f32_e32 vcc, s51, v189
	v_add_f32_e32 v124, v131, v124
	v_add_f32_e32 v124, v120, v124
	v_cndmask_b32_e32 v125, 0, v125, vcc
	v_cmp_lt_f32_e32 vcc, s51, v190
	v_add_f32_e32 v124, v125, v124
	s_nop 0
	v_cndmask_b32_e32 v126, 0, v126, vcc
	v_cmp_lt_f32_e32 vcc, s51, v123
	v_sub_f32_e32 v123, v123, v31
	v_mul_f32_e32 v123, 0x3fb8aa3b, v123
	v_exp_f32_e32 v123, v123
	v_add_f32_e32 v124, v126, v124
	v_cndmask_b32_e32 v127, 0, v123, vcc
	v_cmp_lt_f32_e32 vcc, s51, v116
	v_sub_f32_e32 v116, v116, v31
	v_mul_f32_e32 v116, 0x3fb8aa3b, v116
	v_exp_f32_e32 v116, v116
	v_add_f32_e32 v123, v127, v124
	v_cndmask_b32_e32 v130, 0, v116, vcc
	v_add_f32_e32 v116, v130, v123
	v_sub_f32_e32 v123, v191, v31
	v_mul_f32_e32 v123, 0x3fb8aa3b, v123
	v_exp_f32_e32 v123, v123
	v_cmp_lt_f32_e32 vcc, s51, v191
	s_nop 1
	v_cndmask_b32_e32 v182, 0, v123, vcc
	v_sub_f32_e32 v123, v192, v31
	v_mul_f32_e32 v123, 0x3fb8aa3b, v123
	v_exp_f32_e32 v123, v123
	v_cmp_lt_f32_e32 vcc, s51, v192
	v_add_f32_e32 v116, v182, v116
	s_nop 0
	v_cndmask_b32_e32 v189, 0, v123, vcc
	v_sub_f32_e32 v123, v193, v31
	v_mul_f32_e32 v123, 0x3fb8aa3b, v123
	v_exp_f32_e32 v123, v123
	v_cmp_lt_f32_e32 vcc, s51, v193
	v_add_f32_e32 v116, v189, v116
	s_nop 0
	v_cndmask_b32_e32 v190, 0, v123, vcc
	v_add_f32_e32 v123, v190, v116
	v_exp_f32_e32 v116, v194
	v_mov_b32_e32 v124, v123
	s_nop 1
	v_permlane16_swap_b32_e32 v123, v124
	v_add_f32_e32 v123, v123, v124
	v_mov_b32_e32 v124, v123
	s_nop 1
	v_permlane32_swap_b32_e32 v123, v124
	v_cmp_neq_f32_e32 vcc, 1.0, v116
	s_cbranch_vccz .LBB0_697
	v_pk_mul_f32 v[66:67], v[66:67], v[116:117] op_sel_hi:[1,0]
	v_pk_mul_f32 v[64:65], v[64:65], v[116:117] op_sel_hi:[1,0]
	v_pk_mul_f32 v[62:63], v[62:63], v[116:117] op_sel_hi:[1,0]
	v_pk_mul_f32 v[60:61], v[60:61], v[116:117] op_sel_hi:[1,0]
	v_pk_mul_f32 v[58:59], v[58:59], v[116:117] op_sel_hi:[1,0]
	v_pk_mul_f32 v[56:57], v[56:57], v[116:117] op_sel_hi:[1,0]
	v_pk_mul_f32 v[54:55], v[54:55], v[116:117] op_sel_hi:[1,0]
	v_pk_mul_f32 v[52:53], v[52:53], v[116:117] op_sel_hi:[1,0]
	v_pk_mul_f32 v[50:51], v[50:51], v[116:117] op_sel_hi:[1,0]
	v_pk_mul_f32 v[48:49], v[48:49], v[116:117] op_sel_hi:[1,0]
	v_pk_mul_f32 v[46:47], v[46:47], v[116:117] op_sel_hi:[1,0]
	v_pk_mul_f32 v[44:45], v[44:45], v[116:117] op_sel_hi:[1,0]
	v_pk_mul_f32 v[42:43], v[42:43], v[116:117] op_sel_hi:[1,0]
	v_pk_mul_f32 v[40:41], v[40:41], v[116:117] op_sel_hi:[1,0]
	v_pk_mul_f32 v[38:39], v[38:39], v[116:117] op_sel_hi:[1,0]
	v_pk_mul_f32 v[36:37], v[36:37], v[116:117] op_sel_hi:[1,0]

.LBB0_704:
	s_setprio 1
	ds_read_b128 v[186:189], v178 offset:11328
	ds_read_b128 v[240:243], v178 offset:11392
	ds_read_b128 v[248:251], v178 offset:11456
	ds_read_b128 v[252:255], v178 offset:11520
	s_waitcnt lgkmcnt(3)
	v_mfma_f32_16x16x32_bf16 v[190:193], v[186:189], v[0:3], 0
	v_mfma_f32_16x16x32_bf16 v[128:131], v[186:189], v[16:19], 0
	ds_read_b128 v[186:189], v178 offset:15680
	s_waitcnt lgkmcnt(3)
	v_mfma_f32_16x16x32_bf16 v[190:193], v[240:243], v[4:7], v[190:193]
	v_mfma_f32_16x16x32_bf16 v[128:131], v[240:243], v[20:23], v[128:131]
	ds_read_b128 v[240:243], v178 offset:15744
	s_waitcnt lgkmcnt(3)
	v_mfma_f32_16x16x32_bf16 v[190:193], v[248:251], v[8:11], v[190:193]
	v_mfma_f32_16x16x32_bf16 v[128:131], v[248:251], v[24:27], v[128:131]
	ds_read_b128 v[248:251], v178 offset:15808
	s_waitcnt lgkmcnt(3)
	v_mfma_f32_16x16x32_bf16 v[190:193], v[252:255], v[12:15], v[190:193]
	v_mfma_f32_16x16x32_bf16 v[128:131], v[252:255], v[32:35], v[128:131]
	ds_read_b128 v[252:255], v178 offset:15872
	s_waitcnt lgkmcnt(3)
	v_mfma_f32_16x16x32_bf16 v[140:143], v[186:189], v[0:3], 0
	v_mfma_f32_16x16x32_bf16 v[124:127], v[186:189], v[16:19], 0
	ds_read_b128 v[186:189], v178 offset:20032
	s_waitcnt lgkmcnt(3)
	v_mfma_f32_16x16x32_bf16 v[140:143], v[240:243], v[4:7], v[140:143]
	v_mfma_f32_16x16x32_bf16 v[124:127], v[240:243], v[20:23], v[124:127]
	ds_read_b128 v[240:243], v178 offset:20096
	s_waitcnt lgkmcnt(3)
	v_mfma_f32_16x16x32_bf16 v[140:143], v[248:251], v[8:11], v[140:143]
	v_mfma_f32_16x16x32_bf16 v[124:127], v[248:251], v[24:27], v[124:127]
	ds_read_b128 v[248:251], v178 offset:20160
	s_waitcnt lgkmcnt(3)
	v_mfma_f32_16x16x32_bf16 v[140:143], v[252:255], v[12:15], v[140:143]
	v_mfma_f32_16x16x32_bf16 v[124:127], v[252:255], v[32:35], v[124:127]
	ds_read_b128 v[252:255], v178 offset:20224
	s_waitcnt lgkmcnt(3)
	v_mfma_f32_16x16x32_bf16 v[136:139], v[186:189], v[0:3], 0
	v_mfma_f32_16x16x32_bf16 v[120:123], v[186:189], v[16:19], 0
	ds_read_b128 v[186:189], v178 offset:24384
	s_waitcnt lgkmcnt(3)
	v_mfma_f32_16x16x32_bf16 v[136:139], v[240:243], v[4:7], v[136:139]
	v_mfma_f32_16x16x32_bf16 v[120:123], v[240:243], v[20:23], v[120:123]
	ds_read_b128 v[240:243], v178 offset:24448
	s_waitcnt lgkmcnt(3)
	v_mfma_f32_16x16x32_bf16 v[136:139], v[248:251], v[8:11], v[136:139]
	v_mfma_f32_16x16x32_bf16 v[120:123], v[248:251], v[24:27], v[120:123]
	ds_read_b128 v[248:251], v178 offset:24512
	s_waitcnt lgkmcnt(3)
	v_mfma_f32_16x16x32_bf16 v[136:139], v[252:255], v[12:15], v[136:139]
	v_mfma_f32_16x16x32_bf16 v[120:123], v[252:255], v[32:35], v[120:123]
	ds_read_b128 v[252:255], v178 offset:24576
	s_waitcnt lgkmcnt(3)
	v_mfma_f32_16x16x32_bf16 v[132:135], v[186:189], v[0:3], 0
	v_mfma_f32_16x16x32_bf16 v[116:119], v[186:189], v[16:19], 0
	s_waitcnt lgkmcnt(2)
	v_mfma_f32_16x16x32_bf16 v[132:135], v[240:243], v[4:7], v[132:135]
	v_mfma_f32_16x16x32_bf16 v[116:119], v[240:243], v[20:23], v[116:119]
	s_waitcnt lgkmcnt(1)
	v_mfma_f32_16x16x32_bf16 v[132:135], v[248:251], v[8:11], v[132:135]
	v_mfma_f32_16x16x32_bf16 v[116:119], v[248:251], v[24:27], v[116:119]
	s_waitcnt lgkmcnt(0)
	v_mfma_f32_16x16x32_bf16 v[132:135], v[252:255], v[12:15], v[132:135]
	v_mfma_f32_16x16x32_bf16 v[116:119], v[252:255], v[32:35], v[116:119]
	s_setprio 0
	v_lshl_add_u32 v189, s2, 6, v155
	v_sub_u32_e32 v239, v160, v189
	v_med3_i32 v239, v239, 0, v207
	v_lshl_add_u32 v239, v239, 2, v151
	ds_read_b32 v182, v239 offset:9216
	v_or_b32_e32 v240, 1, v189
	v_sub_u32_e32 v240, v160, v240
	v_med3_i32 v240, v240, 0, v207
	v_lshl_add_u32 v240, v240, 2, v151
	ds_read_b32 v240, v240 offset:9216
	v_or_b32_e32 v241, 2, v189
	v_sub_u32_e32 v241, v160, v241
	v_med3_i32 v241, v241, 0, v207
	v_lshl_add_u32 v241, v241, 2, v151
	ds_read_b32 v241, v241 offset:9216
	v_or_b32_e32 v242, 3, v189
	v_sub_u32_e32 v242, v160, v242
	v_med3_i32 v242, v242, 0, v207
	v_lshl_add_u32 v242, v242, 2, v151
	ds_read_b32 v242, v242 offset:9216
	v_sub_u32_e32 v243, v175, v189
	v_med3_i32 v243, v243, 0, v207
	v_lshl_add_u32 v243, v243, 2, v151
	ds_read_b32 v243, v243 offset:9216
	v_add_u32_e32 v247, 17, v189
	v_sub_u32_e32 v247, v160, v247
	v_med3_i32 v247, v247, 0, v207
	v_lshl_add_u32 v247, v247, 2, v151
	ds_read_b32 v247, v247 offset:9216
	v_add_u32_e32 v248, 18, v189
	v_sub_u32_e32 v248, v160, v248
	v_med3_i32 v248, v248, 0, v207
	v_lshl_add_u32 v248, v248, 2, v151
	ds_read_b32 v248, v248 offset:9216
	v_add_u32_e32 v249, 19, v189
	v_sub_u32_e32 v249, v160, v249
	v_med3_i32 v249, v249, 0, v207
	v_lshl_add_u32 v249, v249, 2, v151
	ds_read_b32 v249, v249 offset:9216
	v_add_u32_e32 v250, 32, v189
	v_sub_u32_e32 v250, v160, v250
	v_med3_i32 v250, v250, 0, v207
	v_lshl_add_u32 v250, v250, 2, v151
	ds_read_b32 v250, v250 offset:9216
	v_add_u32_e32 v251, 33, v189
	v_sub_u32_e32 v251, v160, v251
	v_med3_i32 v251, v251, 0, v207
	v_lshl_add_u32 v251, v251, 2, v151
	ds_read_b32 v251, v251 offset:9216
	v_add_u32_e32 v252, 34, v189
	v_sub_u32_e32 v252, v160, v252
	v_med3_i32 v252, v252, 0, v207
	v_lshl_add_u32 v252, v252, 2, v151
	ds_read_b32 v252, v252 offset:9216
	v_add_u32_e32 v253, 35, v189
	v_sub_u32_e32 v253, v160, v253
	v_med3_i32 v253, v253, 0, v207
	v_lshl_add_u32 v253, v253, 2, v151
	ds_read_b32 v253, v253 offset:9216
	v_add_u32_e32 v254, 48, v189
	v_sub_u32_e32 v254, v160, v254
	v_med3_i32 v254, v254, 0, v207
	v_lshl_add_u32 v254, v254, 2, v151
	ds_read_b32 v254, v254 offset:9216
	v_add_u32_e32 v255, 49, v189
	v_sub_u32_e32 v255, v160, v255
	v_med3_i32 v255, v255, 0, v207
	v_lshl_add_u32 v255, v255, 2, v151
	ds_read_b32 v255, v255 offset:9216
	v_sub_u32_e32 v29, v160, v189
	v_cmp_gt_u32_e64 s[8:9], s75, v29
	v_sub_u32_e32 v187, v175, v189
	v_add_u32_e32 v213, 17, v189
	v_add_u32_e32 v214, 18, v189
	v_add_u32_e32 v215, 19, v189
	s_waitcnt lgkmcnt(13)
	v_add_f32_e32 v29, v190, v182
	v_or_b32_e32 v190, 1, v189
	v_cndmask_b32_e64 v30, v208, v29, s[8:9]
	v_sub_u32_e32 v29, v160, v190
	v_cmp_gt_u32_e32 vcc, s75, v29
	v_add_u32_e32 v216, 32, v189
	v_add_u32_e32 v194, 34, v189
	v_add_u32_e32 v195, 35, v189
	v_add_u32_e32 v209, 48, v189
	s_waitcnt lgkmcnt(12)
	v_add_f32_e32 v29, v191, v240
	v_or_b32_e32 v191, 2, v189
	v_sub_u32_e32 v181, v160, v191
	v_cndmask_b32_e32 v180, v208, v29, vcc
	v_cmp_gt_u32_e32 vcc, s75, v181
	v_add_u32_e32 v210, 49, v189
	v_add_u32_e32 v211, 50, v189
	v_add_u32_e32 v212, 51, v189
	v_max3_f32 v29, v30, s82, v180
	s_waitcnt lgkmcnt(11)
	v_add_f32_e32 v181, v192, v241
	v_or_b32_e32 v192, 3, v189
	v_sub_u32_e32 v186, v160, v192
	v_cndmask_b32_e32 v181, v208, v181, vcc
	v_cmp_gt_u32_e32 vcc, s75, v186
	s_waitcnt lgkmcnt(10)
	v_add_f32_e32 v186, v193, v242
	v_cndmask_b32_e32 v186, v208, v186, vcc
	v_cmp_gt_u32_e32 vcc, s75, v187
	v_add_u32_e32 v193, 33, v189
	v_max3_f32 v29, v29, v181, v186
	s_waitcnt lgkmcnt(9)
	v_add_f32_e32 v140, v140, v243
	v_sub_u32_e32 v187, v160, v213
	v_cndmask_b32_e32 v140, v208, v140, vcc
	v_cmp_gt_u32_e32 vcc, s75, v187
	s_waitcnt lgkmcnt(8)
	v_add_f32_e32 v141, v141, v247
	v_sub_u32_e32 v187, v160, v214
	v_cndmask_b32_e32 v141, v208, v141, vcc
	v_cmp_gt_u32_e32 vcc, s75, v187
	v_max3_f32 v29, v29, v140, v141
	s_waitcnt lgkmcnt(7)
	v_add_f32_e32 v142, v142, v248
	v_cndmask_b32_e32 v187, v208, v142, vcc
	v_sub_u32_e32 v142, v160, v215
	v_cmp_gt_u32_e32 vcc, s75, v142
	s_waitcnt lgkmcnt(6)
	v_add_f32_e32 v142, v143, v249
	v_cndmask_b32_e32 v188, v208, v142, vcc
	v_sub_u32_e32 v142, v160, v216
	v_cmp_gt_u32_e32 vcc, s75, v142
	v_max3_f32 v29, v29, v187, v188
	s_waitcnt lgkmcnt(5)
	v_add_f32_e32 v136, v136, v250
	v_cndmask_b32_e32 v217, v208, v136, vcc
	v_sub_u32_e32 v136, v160, v193
	v_cmp_gt_u32_e32 vcc, s75, v136
	s_waitcnt lgkmcnt(4)
	v_add_f32_e32 v136, v137, v251
	v_cndmask_b32_e32 v218, v208, v136, vcc
	v_sub_u32_e32 v136, v160, v194
	v_cmp_gt_u32_e32 vcc, s75, v136
	v_max3_f32 v29, v29, v217, v218
	s_waitcnt lgkmcnt(3)
	v_add_f32_e32 v136, v138, v252
	v_cndmask_b32_e32 v138, v208, v136, vcc
	v_sub_u32_e32 v136, v160, v195
	v_cmp_gt_u32_e32 vcc, s75, v136
	s_waitcnt lgkmcnt(2)
	v_add_f32_e32 v136, v139, v253
	v_cndmask_b32_e32 v219, v208, v136, vcc
	v_sub_u32_e32 v136, v160, v209
	v_cmp_gt_u32_e32 vcc, s75, v136
	v_max3_f32 v29, v29, v138, v219
	s_waitcnt lgkmcnt(1)
	v_add_f32_e32 v132, v132, v254
	v_cndmask_b32_e32 v220, v208, v132, vcc
	v_sub_u32_e32 v132, v160, v210
	v_cmp_gt_u32_e32 vcc, s75, v132
	s_waitcnt lgkmcnt(0)
	v_add_f32_e32 v132, v133, v255
	v_cndmask_b32_e32 v221, v208, v132, vcc
	v_sub_u32_e32 v132, v160, v211
	v_cmp_gt_u32_e32 vcc, s75, v132
	v_med3_i32 v132, v132, 0, v207
	v_lshl_add_u32 v132, v132, 2, v151
	ds_read_b32 v132, v132 offset:9216
	v_max3_f32 v29, v29, v220, v221
	s_waitcnt lgkmcnt(0)
	v_add_f32_e32 v132, v134, v132
	v_cndmask_b32_e32 v222, v208, v132, vcc
	v_sub_u32_e32 v132, v160, v212
	v_cmp_gt_u32_e32 vcc, s75, v132
	v_med3_i32 v132, v132, 0, v207
	v_lshl_add_u32 v132, v132, 2, v151
	ds_read_b32 v132, v132 offset:9216
	s_waitcnt lgkmcnt(0)
	v_add_f32_e32 v132, v135, v132
	v_cndmask_b32_e32 v223, v208, v132, vcc
	v_max3_f32 v29, v29, v222, v223
	v_mov_b32_e32 v132, v29
	s_nop 1
	v_permlane16_swap_b32_e32 v29, v132
	v_max_f32_e32 v132, v132, v132
	v_max_f32_e32 v29, v29, v29
	v_max_f32_e32 v29, v29, v132
	v_mov_b32_e32 v132, v29
	s_nop 1
	v_permlane32_swap_b32_e32 v29, v132
	v_max3_f32 v29, v183, v29, v132
	v_cmp_lt_f32_e32 vcc, s51, v30
	v_sub_f32_e32 v30, v30, v29
	v_mul_f32_e32 v30, 0x3fb8aa3b, v30
	v_sub_f32_e32 v133, v180, v29
	v_exp_f32_e32 v30, v30
	v_mul_f32_e32 v133, 0x3fb8aa3b, v133
	v_sub_f32_e32 v134, v181, v29
	v_exp_f32_e32 v133, v133
	v_mul_f32_e32 v134, 0x3fb8aa3b, v134
	v_sub_f32_e32 v135, v186, v29
	v_exp_f32_e32 v134, v134
	v_mul_f32_e32 v135, 0x3fb8aa3b, v135
	v_sub_f32_e32 v132, v183, v29
	v_exp_f32_e32 v135, v135
	v_mul_f32_e32 v224, 0x3fb8aa3b, v132
	v_cndmask_b32_e32 v132, 0, v30, vcc
	v_cmp_lt_f32_e32 vcc, s51, v180
	v_sub_f32_e32 v139, v218, v29
	v_mul_f32_e32 v139, 0x3fb8aa3b, v139
	v_cndmask_b32_e32 v133, 0, v133, vcc
	v_cmp_lt_f32_e32 vcc, s51, v181
	v_exp_f32_e32 v139, v139
	v_add_f32_e32 v30, 0, v132
	v_cndmask_b32_e32 v134, 0, v134, vcc
	v_cmp_lt_f32_e32 vcc, s51, v186
	v_add_f32_e32 v30, v133, v30
	v_add_f32_e32 v30, v134, v30
	v_cndmask_b32_e32 v136, 0, v135, vcc
	v_sub_f32_e32 v135, v140, v29
	v_mul_f32_e32 v135, 0x3fb8aa3b, v135
	v_exp_f32_e32 v135, v135
	v_cmp_lt_f32_e32 vcc, s51, v140
	v_add_f32_e32 v30, v136, v30
	s_nop 0
	v_cndmask_b32_e32 v137, 0, v135, vcc
	v_sub_f32_e32 v135, v141, v29
	v_mul_f32_e32 v135, 0x3fb8aa3b, v135
	v_exp_f32_e32 v135, v135
	v_cmp_lt_f32_e32 vcc, s51, v141
	v_add_f32_e32 v30, v137, v30
	s_nop 0
	v_cndmask_b32_e32 v142, 0, v135, vcc
	v_sub_f32_e32 v135, v187, v29
	v_mul_f32_e32 v135, 0x3fb8aa3b, v135
	v_exp_f32_e32 v135, v135
	v_cmp_lt_f32_e32 vcc, s51, v187
	v_add_f32_e32 v30, v142, v30
	s_nop 0
	v_cndmask_b32_e32 v143, 0, v135, vcc
	v_sub_f32_e32 v135, v188, v29
	v_mul_f32_e32 v135, 0x3fb8aa3b, v135
	v_exp_f32_e32 v135, v135
	v_cmp_lt_f32_e32 vcc, s51, v188
	v_add_f32_e32 v30, v143, v30
	s_nop 0
	v_cndmask_b32_e32 v183, 0, v135, vcc
	v_sub_f32_e32 v135, v217, v29
	v_mul_f32_e32 v135, 0x3fb8aa3b, v135
	v_exp_f32_e32 v135, v135
	v_cmp_lt_f32_e32 vcc, s51, v217
	v_add_f32_e32 v30, v183, v30
	s_nop 0
	v_cndmask_b32_e32 v135, 0, v135, vcc
	v_cmp_lt_f32_e32 vcc, s51, v218
	v_add_f32_e32 v30, v135, v30
	s_nop 0
	v_cndmask_b32_e32 v139, 0, v139, vcc
	v_cmp_lt_f32_e32 vcc, s51, v138
	v_sub_f32_e32 v138, v138, v29
	v_mul_f32_e32 v138, 0x3fb8aa3b, v138
	v_exp_f32_e32 v138, v138
	v_add_f32_e32 v30, v139, v30
	v_cndmask_b32_e32 v141, 0, v138, vcc
	v_sub_f32_e32 v138, v219, v29
	v_mul_f32_e32 v138, 0x3fb8aa3b, v138
	v_exp_f32_e32 v138, v138
	v_cmp_lt_f32_e32 vcc, s51, v219
	v_add_f32_e32 v30, v141, v30
	s_nop 0
	v_cndmask_b32_e32 v180, 0, v138, vcc
	v_sub_f32_e32 v138, v220, v29
	v_mul_f32_e32 v138, 0x3fb8aa3b, v138
	v_exp_f32_e32 v138, v138
	v_cmp_lt_f32_e32 vcc, s51, v220
	v_add_f32_e32 v30, v180, v30
	s_nop 0
	v_cndmask_b32_e32 v181, 0, v138, vcc
	v_sub_f32_e32 v138, v221, v29
	v_mul_f32_e32 v138, 0x3fb8aa3b, v138
	v_exp_f32_e32 v138, v138
	v_cmp_lt_f32_e32 vcc, s51, v221
	v_add_f32_e32 v30, v181, v30
	s_nop 0
	v_cndmask_b32_e32 v186, 0, v138, vcc
	v_sub_f32_e32 v138, v222, v29
	v_mul_f32_e32 v138, 0x3fb8aa3b, v138
	v_exp_f32_e32 v138, v138
	v_cmp_lt_f32_e32 vcc, s51, v222
	v_add_f32_e32 v30, v186, v30
	s_nop 0
	v_cndmask_b32_e32 v187, 0, v138, vcc
	v_sub_f32_e32 v138, v223, v29
	v_mul_f32_e32 v138, 0x3fb8aa3b, v138
	v_exp_f32_e32 v138, v138
	v_cmp_lt_f32_e32 vcc, s51, v223
	v_add_f32_e32 v30, v187, v30
	s_nop 0
	v_cndmask_b32_e32 v188, 0, v138, vcc
	v_add_f32_e32 v138, v188, v30
	v_exp_f32_e32 v30, v224
	v_mov_b32_e32 v140, v138
	s_nop 1
	v_permlane16_swap_b32_e32 v138, v140
	v_add_f32_e32 v138, v138, v140
	v_mov_b32_e32 v140, v138
	s_nop 1
	v_permlane32_swap_b32_e32 v138, v140
	v_cmp_neq_f32_e32 vcc, 1.0, v30
	s_cbranch_vccz .LBB0_706
	v_pk_mul_f32 v[98:99], v[98:99], v[30:31] op_sel_hi:[1,0]
	v_pk_mul_f32 v[96:97], v[96:97], v[30:31] op_sel_hi:[1,0]
	v_pk_mul_f32 v[94:95], v[94:95], v[30:31] op_sel_hi:[1,0]
	v_pk_mul_f32 v[92:93], v[92:93], v[30:31] op_sel_hi:[1,0]
	v_pk_mul_f32 v[90:91], v[90:91], v[30:31] op_sel_hi:[1,0]
	v_pk_mul_f32 v[88:89], v[88:89], v[30:31] op_sel_hi:[1,0]
	v_pk_mul_f32 v[86:87], v[86:87], v[30:31] op_sel_hi:[1,0]
	v_pk_mul_f32 v[84:85], v[84:85], v[30:31] op_sel_hi:[1,0]
	v_pk_mul_f32 v[82:83], v[82:83], v[30:31] op_sel_hi:[1,0]
	v_pk_mul_f32 v[80:81], v[80:81], v[30:31] op_sel_hi:[1,0]
	v_pk_mul_f32 v[78:79], v[78:79], v[30:31] op_sel_hi:[1,0]
	v_pk_mul_f32 v[76:77], v[76:77], v[30:31] op_sel_hi:[1,0]
	v_pk_mul_f32 v[74:75], v[74:75], v[30:31] op_sel_hi:[1,0]
	v_pk_mul_f32 v[72:73], v[72:73], v[30:31] op_sel_hi:[1,0]
	v_pk_mul_f32 v[70:71], v[70:71], v[30:31] op_sel_hi:[1,0]
	v_pk_mul_f32 v[68:69], v[68:69], v[30:31] op_sel_hi:[1,0]
.LBB0_706:
	v_sub_u32_e32 v239, v156, v189
	v_med3_i32 v239, v239, 0, v207
	v_lshl_add_u32 v239, v239, 2, v151
	ds_read_b32 v239, v239 offset:9216
	v_sub_u32_e32 v240, v156, v190
	v_med3_i32 v240, v240, 0, v207
	v_lshl_add_u32 v240, v240, 2, v151
	ds_read_b32 v240, v240 offset:9216
	v_sub_u32_e32 v241, v156, v191
	v_med3_i32 v241, v241, 0, v207
	v_lshl_add_u32 v241, v241, 2, v151
	ds_read_b32 v241, v241 offset:9216
	v_sub_u32_e32 v242, v156, v192
	v_med3_i32 v242, v242, 0, v207
	v_lshl_add_u32 v242, v242, 2, v151
	ds_read_b32 v242, v242 offset:9216
	v_sub_u32_e32 v243, v156, v213
	v_med3_i32 v243, v243, 0, v207
	v_lshl_add_u32 v243, v243, 2, v151
	ds_read_b32 v243, v243 offset:9216
	v_sub_u32_e32 v247, v156, v214
	v_med3_i32 v247, v247, 0, v207
	v_lshl_add_u32 v247, v247, 2, v151
	ds_read_b32 v247, v247 offset:9216
	v_sub_u32_e32 v248, v156, v215
	v_med3_i32 v248, v248, 0, v207
	v_lshl_add_u32 v248, v248, 2, v151
	ds_read_b32 v248, v248 offset:9216
	v_sub_u32_e32 v249, v156, v216
	v_med3_i32 v249, v249, 0, v207
	v_lshl_add_u32 v249, v249, 2, v151
	ds_read_b32 v249, v249 offset:9216
	v_sub_u32_e32 v250, v156, v193
	v_med3_i32 v250, v250, 0, v207
	v_lshl_add_u32 v250, v250, 2, v151
	ds_read_b32 v250, v250 offset:9216
	v_sub_u32_e32 v251, v156, v194
	v_med3_i32 v251, v251, 0, v207
	v_lshl_add_u32 v251, v251, 2, v151
	ds_read_b32 v251, v251 offset:9216
	v_sub_u32_e32 v252, v156, v195
	v_med3_i32 v252, v252, 0, v207
	v_lshl_add_u32 v252, v252, 2, v151
	ds_read_b32 v252, v252 offset:9216
	v_sub_u32_e32 v253, v156, v209
	v_med3_i32 v253, v253, 0, v207
	v_lshl_add_u32 v253, v253, 2, v151
	ds_read_b32 v253, v253 offset:9216
	v_sub_u32_e32 v254, v156, v210
	v_med3_i32 v254, v254, 0, v207
	v_lshl_add_u32 v254, v254, 2, v151
	ds_read_b32 v254, v254 offset:9216
	v_sub_u32_e32 v255, v156, v211
	v_med3_i32 v255, v255, 0, v207
	v_lshl_add_u32 v255, v255, 2, v151
	ds_read_b32 v255, v255 offset:9216
	v_sub_u32_e32 v189, v156, v189
	v_cmp_gt_u32_e32 vcc, s75, v189
	v_add_f32_e32 v124, v124, v182
	v_sub_u32_e32 v182, v156, v213
	v_cndmask_b32_e64 v124, v208, v124, s[8:9]
	s_waitcnt lgkmcnt(13)
	v_add_f32_e32 v128, v128, v239
	v_sub_u32_e32 v189, v156, v190
	v_cndmask_b32_e32 v128, v208, v128, vcc
	v_cmp_gt_u32_e32 vcc, s75, v189
	v_sub_u32_e32 v190, v156, v191
	s_waitcnt lgkmcnt(12)
	v_add_f32_e32 v129, v129, v240
	v_cndmask_b32_e32 v129, v208, v129, vcc
	v_cmp_gt_u32_e32 vcc, s75, v190
	v_max3_f32 v189, v128, s82, v129
	s_waitcnt lgkmcnt(11)
	v_add_f32_e32 v130, v130, v241
	v_sub_u32_e32 v190, v156, v192
	v_cndmask_b32_e32 v130, v208, v130, vcc
	v_cmp_gt_u32_e32 vcc, s75, v190
	s_waitcnt lgkmcnt(10)
	v_add_f32_e32 v131, v131, v242
	v_cndmask_b32_e32 v131, v208, v131, vcc
	v_cmp_gt_u32_e32 vcc, s75, v182
	v_max3_f32 v189, v189, v130, v131
	s_waitcnt lgkmcnt(9)
	v_add_f32_e32 v125, v125, v243
	v_cndmask_b32_e32 v125, v208, v125, vcc
	v_max3_f32 v182, v189, v124, v125
	v_sub_u32_e32 v189, v156, v214
	v_cmp_gt_u32_e32 vcc, s75, v189
	s_waitcnt lgkmcnt(8)
	v_add_f32_e32 v126, v126, v247
	v_sub_u32_e32 v189, v156, v215
	v_cndmask_b32_e32 v126, v208, v126, vcc
	v_cmp_gt_u32_e32 vcc, s75, v189
	s_waitcnt lgkmcnt(7)
	v_add_f32_e32 v127, v127, v248
	v_sub_u32_e32 v189, v156, v216
	v_cndmask_b32_e32 v127, v208, v127, vcc
	v_cmp_gt_u32_e32 vcc, s75, v189
	v_max3_f32 v182, v182, v126, v127
	s_waitcnt lgkmcnt(6)
	v_add_f32_e32 v120, v120, v249
	v_cndmask_b32_e32 v189, v208, v120, vcc
	v_sub_u32_e32 v120, v156, v193
	v_cmp_gt_u32_e32 vcc, s75, v120
	s_waitcnt lgkmcnt(5)
	v_add_f32_e32 v120, v121, v250
	v_sub_u32_e32 v121, v156, v194
	v_cndmask_b32_e32 v190, v208, v120, vcc
	v_cmp_gt_u32_e32 vcc, s75, v121
	v_max3_f32 v120, v182, v189, v190
	s_waitcnt lgkmcnt(4)
	v_add_f32_e32 v121, v122, v251
	v_cndmask_b32_e32 v191, v208, v121, vcc
	v_sub_u32_e32 v121, v156, v195
	v_cmp_gt_u32_e32 vcc, s75, v121
	s_waitcnt lgkmcnt(3)
	v_add_f32_e32 v121, v123, v252
	v_cndmask_b32_e32 v192, v208, v121, vcc
	v_sub_u32_e32 v121, v156, v209
	v_cmp_gt_u32_e32 vcc, s75, v121
	v_max3_f32 v120, v120, v191, v192
	s_waitcnt lgkmcnt(2)
	v_add_f32_e32 v116, v116, v253
	v_sub_u32_e32 v121, v156, v210
	v_cndmask_b32_e32 v116, v208, v116, vcc
	v_cmp_gt_u32_e32 vcc, s75, v121
	s_waitcnt lgkmcnt(1)
	v_add_f32_e32 v117, v117, v254
	v_cndmask_b32_e32 v193, v208, v117, vcc
	v_max3_f32 v117, v120, v116, v193
	v_sub_u32_e32 v120, v156, v211
	v_cmp_gt_u32_e32 vcc, s75, v120
	s_waitcnt lgkmcnt(0)
	v_add_f32_e32 v118, v118, v255
	v_cndmask_b32_e32 v194, v208, v118, vcc
	v_sub_u32_e32 v118, v156, v212
	v_cmp_gt_u32_e32 vcc, s75, v118
	v_med3_i32 v118, v118, 0, v207
	v_lshl_add_u32 v118, v118, 2, v151
	ds_read_b32 v118, v118 offset:9216
	s_waitcnt lgkmcnt(0)
	v_add_f32_e32 v118, v119, v118
	v_cndmask_b32_e32 v195, v208, v118, vcc
	v_max3_f32 v117, v117, v194, v195
	v_mov_b32_e32 v118, v117
	s_nop 1
	v_permlane16_swap_b32_e32 v117, v118
	v_max_f32_e32 v118, v118, v118
	v_max_f32_e32 v117, v117, v117
	v_max_f32_e32 v117, v117, v118
	v_mov_b32_e32 v118, v117
	s_nop 1
	v_permlane32_swap_b32_e32 v117, v118
	v_max3_f32 v182, v31, v117, v118
	v_sub_f32_e32 v31, v31, v182
	v_mul_f32_e32 v209, 0x3fb8aa3b, v31
	v_sub_f32_e32 v31, v128, v182
	v_mul_f32_e32 v31, 0x3fb8aa3b, v31
	v_sub_f32_e32 v117, v129, v182
	v_exp_f32_e32 v31, v31
	v_mul_f32_e32 v117, 0x3fb8aa3b, v117
	v_exp_f32_e32 v117, v117
	v_cmp_lt_f32_e32 vcc, s51, v128
	v_sub_f32_e32 v120, v131, v182
	v_mul_f32_e32 v120, 0x3fb8aa3b, v120
	v_cndmask_b32_e32 v31, 0, v31, vcc
	v_cmp_lt_f32_e32 vcc, s51, v129
	v_add_f32_e32 v118, 0, v31
	v_sub_f32_e32 v121, v124, v182
	v_cndmask_b32_e32 v117, 0, v117, vcc
	v_add_f32_e32 v119, v117, v118
	v_sub_f32_e32 v118, v130, v182
	v_mul_f32_e32 v118, 0x3fb8aa3b, v118
	v_exp_f32_e32 v118, v118
	v_exp_f32_e32 v120, v120
	v_mul_f32_e32 v121, 0x3fb8aa3b, v121
	v_sub_f32_e32 v122, v125, v182
	v_exp_f32_e32 v121, v121
	v_mul_f32_e32 v122, 0x3fb8aa3b, v122
	v_cmp_lt_f32_e32 vcc, s51, v130
	v_exp_f32_e32 v122, v122
	s_nop 0
	v_cndmask_b32_e32 v118, 0, v118, vcc
	v_cmp_lt_f32_e32 vcc, s51, v131
	v_add_f32_e32 v119, v118, v119
	s_nop 0
	v_cndmask_b32_e32 v120, 0, v120, vcc
	v_cmp_lt_f32_e32 vcc, s51, v124
	v_add_f32_e32 v119, v120, v119
	s_nop 0
	v_cndmask_b32_e32 v121, 0, v121, vcc
	v_cmp_lt_f32_e32 vcc, s51, v125
	v_add_f32_e32 v119, v121, v119
	v_sub_f32_e32 v125, v192, v182
	v_cndmask_b32_e32 v128, 0, v122, vcc
	v_sub_f32_e32 v122, v126, v182
	v_mul_f32_e32 v122, 0x3fb8aa3b, v122
	v_exp_f32_e32 v122, v122
	v_cmp_lt_f32_e32 vcc, s51, v126
	v_add_f32_e32 v119, v128, v119
	v_mul_f32_e32 v125, 0x3fb8aa3b, v125
	v_cndmask_b32_e32 v126, 0, v122, vcc
	v_sub_f32_e32 v122, v127, v182
	v_mul_f32_e32 v122, 0x3fb8aa3b, v122
	v_exp_f32_e32 v122, v122
	v_cmp_lt_f32_e32 vcc, s51, v127
	v_add_f32_e32 v119, v126, v119
	v_exp_f32_e32 v125, v125
	v_cndmask_b32_e32 v130, 0, v122, vcc
	v_add_f32_e32 v122, v130, v119
	v_sub_f32_e32 v119, v189, v182
	v_mul_f32_e32 v119, 0x3fb8aa3b, v119
	v_exp_f32_e32 v119, v119
	v_cmp_lt_f32_e32 vcc, s51, v189
	s_nop 1
	v_cndmask_b32_e32 v119, 0, v119, vcc
	v_add_f32_e32 v123, v119, v122
	v_sub_f32_e32 v122, v190, v182
	v_mul_f32_e32 v122, 0x3fb8aa3b, v122
	v_exp_f32_e32 v122, v122
	v_cmp_lt_f32_e32 vcc, s51, v190
	s_nop 1
	v_cndmask_b32_e32 v122, 0, v122, vcc
	v_add_f32_e32 v124, v122, v123
	v_sub_f32_e32 v123, v191, v182
	v_mul_f32_e32 v123, 0x3fb8aa3b, v123
	v_exp_f32_e32 v123, v123
	v_cmp_lt_f32_e32 vcc, s51, v191
	s_nop 1
	v_cndmask_b32_e32 v123, 0, v123, vcc
	v_cmp_lt_f32_e32 vcc, s51, v192
	v_add_f32_e32 v124, v123, v124
	s_nop 0
	v_cndmask_b32_e32 v127, 0, v125, vcc
	v_cmp_lt_f32_e32 vcc, s51, v116
	v_sub_f32_e32 v116, v116, v182
	v_mul_f32_e32 v116, 0x3fb8aa3b, v116
	v_exp_f32_e32 v116, v116
	v_add_f32_e32 v124, v127, v124
	v_cndmask_b32_e32 v129, 0, v116, vcc
	v_add_f32_e32 v116, v129, v124
	v_sub_f32_e32 v124, v193, v182
	v_mul_f32_e32 v124, 0x3fb8aa3b, v124
	v_exp_f32_e32 v124, v124
	v_cmp_lt_f32_e32 vcc, s51, v193
	s_nop 1
	v_cndmask_b32_e32 v131, 0, v124, vcc
	v_sub_f32_e32 v124, v194, v182
	v_mul_f32_e32 v124, 0x3fb8aa3b, v124
	v_exp_f32_e32 v124, v124
	v_cmp_lt_f32_e32 vcc, s51, v194
	v_add_f32_e32 v116, v131, v116
	s_nop 0
	v_cndmask_b32_e32 v189, 0, v124, vcc
	v_sub_f32_e32 v124, v195, v182
	v_mul_f32_e32 v124, 0x3fb8aa3b, v124
	v_exp_f32_e32 v124, v124
	v_cmp_lt_f32_e32 vcc, s51, v195
	v_add_f32_e32 v116, v189, v116
	s_nop 0
	v_cndmask_b32_e32 v190, 0, v124, vcc
	v_add_f32_e32 v124, v190, v116
	v_exp_f32_e32 v116, v209
	v_mov_b32_e32 v125, v124
	s_nop 1
	v_permlane16_swap_b32_e32 v124, v125
	v_add_f32_e32 v124, v124, v125
	v_mov_b32_e32 v125, v124
	s_nop 1
	v_permlane32_swap_b32_e32 v124, v125
	v_cmp_neq_f32_e32 vcc, 1.0, v116
	s_cbranch_vccz .LBB0_708
	v_pk_mul_f32 v[66:67], v[66:67], v[116:117] op_sel_hi:[1,0]
	v_pk_mul_f32 v[64:65], v[64:65], v[116:117] op_sel_hi:[1,0]
	v_pk_mul_f32 v[62:63], v[62:63], v[116:117] op_sel_hi:[1,0]
	v_pk_mul_f32 v[60:61], v[60:61], v[116:117] op_sel_hi:[1,0]
	v_pk_mul_f32 v[58:59], v[58:59], v[116:117] op_sel_hi:[1,0]
	v_pk_mul_f32 v[56:57], v[56:57], v[116:117] op_sel_hi:[1,0]
	v_pk_mul_f32 v[54:55], v[54:55], v[116:117] op_sel_hi:[1,0]
	v_pk_mul_f32 v[52:53], v[52:53], v[116:117] op_sel_hi:[1,0]
	v_pk_mul_f32 v[50:51], v[50:51], v[116:117] op_sel_hi:[1,0]
	v_pk_mul_f32 v[48:49], v[48:49], v[116:117] op_sel_hi:[1,0]
	v_pk_mul_f32 v[46:47], v[46:47], v[116:117] op_sel_hi:[1,0]
	v_pk_mul_f32 v[44:45], v[44:45], v[116:117] op_sel_hi:[1,0]
	v_pk_mul_f32 v[42:43], v[42:43], v[116:117] op_sel_hi:[1,0]
	v_pk_mul_f32 v[40:41], v[40:41], v[116:117] op_sel_hi:[1,0]
	v_pk_mul_f32 v[38:39], v[38:39], v[116:117] op_sel_hi:[1,0]
	v_pk_mul_f32 v[36:37], v[36:37], v[116:117] op_sel_hi:[1,0]
